# thin kv tile: idle loader waves delay their k+2 stage LDS-DMA issue with s_sleep 6 (staggered behind the MFMA-computing waves)
# baseline (speedup 1.0000x reference)
; #define GLDS16(gp, lp) __builtin_amdgcn_global_load_lds((const unsigned*)(gp), (__attribute__((address_space(3))) unsigned*)(lp), 16, 0, 0)
; template <bool SWAP, class Epi, bool THIN = false> ...
;     ...
;     for (int st = 0; st < ns; ++st) {
;       asm volatile("s_waitcnt vmcnt(0)" ::: "memory");
;       __builtin_amdgcn_s_barrier();
;       asm volatile("" ::: "memory");
;       if (st + 1 < ns) {
;         char* nb = smem + ((st + 1) & 1) * 65536;
;         const int ko = (st + 1) * 64;
; #pragma unroll
;         for (int i = 0; i < 4; ++i) { GLDS16(A + (size_t)(ap[i] + ko), nb + tid * 16 + i * 8192); GLDS16(Bt + (size_t)(bp[i] + ko), nb + 32768 + tid * 16 + i * 8192); }
;       }
;       const char* sa = smem + (st & 1) * 65536 + (wr * 64 + fr) * 128;
;       const char* sb = smem + (st & 1) * 65536 + 32768 + (wc * 128 + fr) * 128;
;       if constexpr (THIN) {
;         if (wc == 0) {
; #pragma unroll
;           for (int ks = 0; ks < 2; ++ks) {
;             bf16x8 af[4], bf[2];
; #pragma unroll
;             for (int m = 0; m < 4; ++m) af[m] = *(const bf16x8*)(sa + m * 2048 + (((ks * 4 + fq) ^ swz) << 4));
; #pragma unroll
;             for (int n = 0; n < 2; ++n) bf[n] = *(const bf16x8*)(sb + n * 2048 + (((ks * 4 + fq) ^ swz) << 4));
; #pragma unroll
;             for (int m = 0; m < 4; ++m)
; #pragma unroll
;               for (int n = 0; n < 2; ++n)
;                 acc[m][n] = SWAP ? __builtin_amdgcn_mfma_f32_16x16x32_bf16(bf[n], af[m], acc[m][n], 0, 0, 0)
;                                  : __builtin_amdgcn_mfma_f32_16x16x32_bf16(af[m], bf[n], acc[m][n], 0, 0, 0);
;           }
;         }
.LBB0_1527:
	s_or_b64 exec, exec, s[6:7]
	s_waitcnt vmcnt(5)
	s_barrier
	s_cmp_eq_u64 s[4:5], 0
	s_cbranch_scc0 .Lthin_ns_1
	s_sleep 6
.Lthin_ns_1:
	v_readfirstlane_b32 s6, v56
	s_add_i32 m0, s6, 0x0
	v_lshl_add_u64 v[4:5], v[46:47], 0, s[26:27]
	global_load_lds_dwordx4 v[4:5], off
	v_or_b32_e32 v2, 0xc0, v38
	s_add_i32 m0, s6, 0x8000
	v_lshl_add_u64 v[4:5], v[2:3], 1, s[18:19]
	global_load_lds_dwordx4 v[4:5], off
	s_add_i32 m0, s6, 0x2000
	v_lshl_add_u64 v[4:5], v[48:49], 0, s[26:27]
	global_load_lds_dwordx4 v[4:5], off
	s_add_i32 m0, s6, 0x4000
	v_lshl_add_u64 v[4:5], v[50:51], 0, s[26:27]
	global_load_lds_dwordx4 v[4:5], off
	s_add_i32 m0, s6, 0x6000
	v_lshl_add_u64 v[4:5], v[52:53], 0, s[26:27]
	global_load_lds_dwordx4 v[4:5], off
	s_and_saveexec_b64 s[6:7], s[4:5]
	s_cbranch_execz .LBB0_1529
	ds_read_b128 v[94:97], v87
	ds_read_b128 v[98:101], v87 offset:2048
	ds_read_b128 v[102:105], v86
	ds_read_b128 v[106:109], v86 offset:2048
	s_waitcnt lgkmcnt(0)
	v_mfma_f32_16x16x32_bf16 v[34:37], v[94:97], v[102:105], v[34:37]
	v_mfma_f32_16x16x32_bf16 v[30:33], v[98:101], v[102:105], v[30:33]
	v_mfma_f32_16x16x32_bf16 v[26:29], v[94:97], v[106:109], v[26:29]
	v_mfma_f32_16x16x32_bf16 v[22:25], v[98:101], v[106:109], v[22:25]
	ds_read_b128 v[102:105], v86 offset:4096
	ds_read_b128 v[106:109], v86 offset:6144
	s_waitcnt lgkmcnt(0)
	v_mfma_f32_16x16x32_bf16 v[18:21], v[94:97], v[102:105], v[18:21]
	v_mfma_f32_16x16x32_bf16 v[10:13], v[94:97], v[106:109], v[10:13]
	ds_read_b128 v[94:97], v89
	v_mfma_f32_16x16x32_bf16 v[14:17], v[98:101], v[102:105], v[14:17]
	v_mfma_f32_16x16x32_bf16 v[4:7], v[98:101], v[106:109], v[6:9]
	ds_read_b128 v[98:101], v89 offset:2048
	ds_read_b128 v[102:105], v88
	ds_read_b128 v[106:109], v88 offset:2048
	s_waitcnt lgkmcnt(0)
	v_mfma_f32_16x16x32_bf16 v[34:37], v[94:97], v[102:105], v[34:37]
	v_mfma_f32_16x16x32_bf16 v[30:33], v[98:101], v[102:105], v[30:33]
	v_mfma_f32_16x16x32_bf16 v[26:29], v[94:97], v[106:109], v[26:29]
	v_mfma_f32_16x16x32_bf16 v[22:25], v[98:101], v[106:109], v[22:25]
	ds_read_b128 v[102:105], v88 offset:4096
	ds_read_b128 v[106:109], v88 offset:6144
	s_waitcnt lgkmcnt(0)
	v_mfma_f32_16x16x32_bf16 v[18:21], v[94:97], v[102:105], v[18:21]
	v_mfma_f32_16x16x32_bf16 v[14:17], v[98:101], v[102:105], v[14:17]
	v_mfma_f32_16x16x32_bf16 v[10:13], v[94:97], v[106:109], v[10:13]
	v_mfma_f32_16x16x32_bf16 v[6:9], v[98:101], v[106:109], v[4:7]

; #define GLDS16(gp, lp) __builtin_amdgcn_global_load_lds((const unsigned*)(gp), (__attribute__((address_space(3))) unsigned*)(lp), 16, 0, 0)
; template <bool SWAP, class Epi, bool THIN = false> ...
;     ...
;     for (int st = 0; st < ns; ++st) {
;       asm volatile("s_waitcnt vmcnt(0)" ::: "memory");
;       __builtin_amdgcn_s_barrier();
;       asm volatile("" ::: "memory");
;       if (st + 1 < ns) {
;         char* nb = smem + ((st + 1) & 1) * 65536;
;         const int ko = (st + 1) * 64;
; #pragma unroll
;         for (int i = 0; i < 4; ++i) { GLDS16(A + (size_t)(ap[i] + ko), nb + tid * 16 + i * 8192); GLDS16(Bt + (size_t)(bp[i] + ko), nb + 32768 + tid * 16 + i * 8192); }
;       }
;       const char* sa = smem + (st & 1) * 65536 + (wr * 64 + fr) * 128;
;       const char* sb = smem + (st & 1) * 65536 + 32768 + (wc * 128 + fr) * 128;
;       if constexpr (THIN) {
;         if (wc == 0) {
; #pragma unroll
;           for (int ks = 0; ks < 2; ++ks) {
;             bf16x8 af[4], bf[2];
; #pragma unroll
;             for (int m = 0; m < 4; ++m) af[m] = *(const bf16x8*)(sa + m * 2048 + (((ks * 4 + fq) ^ swz) << 4));
; #pragma unroll
;             for (int n = 0; n < 2; ++n) bf[n] = *(const bf16x8*)(sb + n * 2048 + (((ks * 4 + fq) ^ swz) << 4));
; #pragma unroll
;             for (int m = 0; m < 4; ++m)
; #pragma unroll
;               for (int n = 0; n < 2; ++n)
;                 acc[m][n] = SWAP ? __builtin_amdgcn_mfma_f32_16x16x32_bf16(bf[n], af[m], acc[m][n], 0, 0, 0)
;                                  : __builtin_amdgcn_mfma_f32_16x16x32_bf16(af[m], bf[n], acc[m][n], 0, 0, 0);
;           }
;         }
.Lthin_ns_2:
	v_readfirstlane_b32 s6, v56
	s_add_i32 m0, s6, 0x10000
	v_lshl_add_u64 v[4:5], v[46:47], 0, s[28:29]
	global_load_lds_dwordx4 v[4:5], off
	v_or_b32_e32 v2, 0x100, v38
	s_add_i32 m0, s6, 0x18000
	v_lshl_add_u64 v[4:5], v[2:3], 1, s[18:19]
	global_load_lds_dwordx4 v[4:5], off
	s_add_i32 m0, s6, 0x12000
	v_lshl_add_u64 v[4:5], v[48:49], 0, s[28:29]
	global_load_lds_dwordx4 v[4:5], off
	s_add_i32 m0, s6, 0x14000
	v_lshl_add_u64 v[4:5], v[50:51], 0, s[28:29]
	global_load_lds_dwordx4 v[4:5], off
	s_add_i32 m0, s6, 0x16000
	v_lshl_add_u64 v[4:5], v[52:53], 0, s[28:29]
	global_load_lds_dwordx4 v[4:5], off
	s_and_saveexec_b64 s[6:7], s[4:5]
	s_cbranch_execz .LBB0_1531
	ds_read_b128 v[94:97], v119 offset:32768
	ds_read_b128 v[98:101], v119 offset:34816
	ds_read_b128 v[102:105], v118
	ds_read_b128 v[106:109], v118 offset:2048
	s_waitcnt lgkmcnt(0)
	v_mfma_f32_16x16x32_bf16 v[34:37], v[94:97], v[102:105], v[34:37]
	v_mfma_f32_16x16x32_bf16 v[30:33], v[98:101], v[102:105], v[30:33]
	v_mfma_f32_16x16x32_bf16 v[26:29], v[94:97], v[106:109], v[26:29]
	v_mfma_f32_16x16x32_bf16 v[22:25], v[98:101], v[106:109], v[22:25]
	ds_read_b128 v[102:105], v118 offset:4096
	ds_read_b128 v[106:109], v118 offset:6144
	s_waitcnt lgkmcnt(0)
	v_mfma_f32_16x16x32_bf16 v[18:21], v[94:97], v[102:105], v[18:21]
	v_mfma_f32_16x16x32_bf16 v[10:13], v[94:97], v[106:109], v[10:13]
	ds_read_b128 v[94:97], v121 offset:32768
	v_mfma_f32_16x16x32_bf16 v[14:17], v[98:101], v[102:105], v[14:17]
	v_mfma_f32_16x16x32_bf16 v[4:7], v[98:101], v[106:109], v[6:9]
	ds_read_b128 v[98:101], v121 offset:34816
	ds_read_b128 v[102:105], v120
	ds_read_b128 v[106:109], v120 offset:2048
	s_waitcnt lgkmcnt(0)
	v_mfma_f32_16x16x32_bf16 v[34:37], v[94:97], v[102:105], v[34:37]
	v_mfma_f32_16x16x32_bf16 v[30:33], v[98:101], v[102:105], v[30:33]
	v_mfma_f32_16x16x32_bf16 v[26:29], v[94:97], v[106:109], v[26:29]
	v_mfma_f32_16x16x32_bf16 v[22:25], v[98:101], v[106:109], v[22:25]
	ds_read_b128 v[102:105], v120 offset:4096
	ds_read_b128 v[106:109], v120 offset:6144
	s_waitcnt lgkmcnt(0)
	v_mfma_f32_16x16x32_bf16 v[18:21], v[94:97], v[102:105], v[18:21]
	v_mfma_f32_16x16x32_bf16 v[14:17], v[98:101], v[102:105], v[14:17]
	v_mfma_f32_16x16x32_bf16 v[10:13], v[94:97], v[106:109], v[10:13]
	v_mfma_f32_16x16x32_bf16 v[6:9], v[98:101], v[106:109], v[4:7]

; #define GLDS16(gp, lp) __builtin_amdgcn_global_load_lds((const unsigned*)(gp), (__attribute__((address_space(3))) unsigned*)(lp), 16, 0, 0)
; template <bool SWAP, class Epi, bool THIN = false> ...
;     ...
;     for (int st = 0; st < ns; ++st) {
;       asm volatile("s_waitcnt vmcnt(0)" ::: "memory");
;       __builtin_amdgcn_s_barrier();
;       asm volatile("" ::: "memory");
;       if (st + 1 < ns) {
;         char* nb = smem + ((st + 1) & 1) * 65536;
;         const int ko = (st + 1) * 64;
; #pragma unroll
;         for (int i = 0; i < 4; ++i) { GLDS16(A + (size_t)(ap[i] + ko), nb + tid * 16 + i * 8192); GLDS16(Bt + (size_t)(bp[i] + ko), nb + 32768 + tid * 16 + i * 8192); }
;       }
;       const char* sa = smem + (st & 1) * 65536 + (wr * 64 + fr) * 128;
;       const char* sb = smem + (st & 1) * 65536 + 32768 + (wc * 128 + fr) * 128;
;       if constexpr (THIN) {
;         if (wc == 0) {
; #pragma unroll
;           for (int ks = 0; ks < 2; ++ks) {
;             bf16x8 af[4], bf[2];
; #pragma unroll
;             for (int m = 0; m < 4; ++m) af[m] = *(const bf16x8*)(sa + m * 2048 + (((ks * 4 + fq) ^ swz) << 4));
; #pragma unroll
;             for (int n = 0; n < 2; ++n) bf[n] = *(const bf16x8*)(sb + n * 2048 + (((ks * 4 + fq) ^ swz) << 4));
; #pragma unroll
;             for (int m = 0; m < 4; ++m)
; #pragma unroll
;               for (int n = 0; n < 2; ++n)
;                 acc[m][n] = SWAP ? __builtin_amdgcn_mfma_f32_16x16x32_bf16(bf[n], af[m], acc[m][n], 0, 0, 0)
;                                  : __builtin_amdgcn_mfma_f32_16x16x32_bf16(af[m], bf[n], acc[m][n], 0, 0, 0);
;           }
;         }
.Lthin_ns_3:
	v_readfirstlane_b32 s6, v56
	s_add_i32 m0, s6, 0x1a000
	v_lshl_add_u64 v[4:5], v[46:47], 0, s[38:39]
	global_load_lds_dwordx4 v[4:5], off
	v_or_b32_e32 v2, 0x140, v38
	s_add_i32 m0, s6, 0x22000
	v_lshl_add_u64 v[4:5], v[2:3], 1, s[18:19]
	global_load_lds_dwordx4 v[4:5], off
	s_add_i32 m0, s6, 0x1c000
	v_lshl_add_u64 v[4:5], v[48:49], 0, s[38:39]
	global_load_lds_dwordx4 v[4:5], off
	s_add_i32 m0, s6, 0x1e000
	v_lshl_add_u64 v[4:5], v[50:51], 0, s[38:39]
	global_load_lds_dwordx4 v[4:5], off
	s_add_i32 m0, s6, 0x20000
	v_lshl_add_u64 v[4:5], v[52:53], 0, s[38:39]
	global_load_lds_dwordx4 v[4:5], off
	s_and_saveexec_b64 s[6:7], s[4:5]
	s_cbranch_execz .LBB0_1533
	ds_read_b128 v[94:97], v83 offset:32768
	ds_read_b128 v[98:101], v83 offset:34816
	ds_read_b128 v[102:105], v82
	ds_read_b128 v[106:109], v82 offset:2048
	s_waitcnt lgkmcnt(0)
	v_mfma_f32_16x16x32_bf16 v[34:37], v[94:97], v[102:105], v[34:37]
	v_mfma_f32_16x16x32_bf16 v[30:33], v[98:101], v[102:105], v[30:33]
	v_mfma_f32_16x16x32_bf16 v[26:29], v[94:97], v[106:109], v[26:29]
	v_mfma_f32_16x16x32_bf16 v[22:25], v[98:101], v[106:109], v[22:25]
	ds_read_b128 v[102:105], v82 offset:4096
	ds_read_b128 v[106:109], v82 offset:6144
	s_waitcnt lgkmcnt(0)
	v_mfma_f32_16x16x32_bf16 v[18:21], v[94:97], v[102:105], v[18:21]
	v_mfma_f32_16x16x32_bf16 v[10:13], v[94:97], v[106:109], v[10:13]
	ds_read_b128 v[94:97], v85 offset:32768
	v_mfma_f32_16x16x32_bf16 v[14:17], v[98:101], v[102:105], v[14:17]
	v_mfma_f32_16x16x32_bf16 v[4:7], v[98:101], v[106:109], v[6:9]
	ds_read_b128 v[98:101], v85 offset:34816
	ds_read_b128 v[102:105], v84
	ds_read_b128 v[106:109], v84 offset:2048
	s_waitcnt lgkmcnt(0)
	v_mfma_f32_16x16x32_bf16 v[34:37], v[94:97], v[102:105], v[34:37]
	v_mfma_f32_16x16x32_bf16 v[30:33], v[98:101], v[102:105], v[30:33]
	v_mfma_f32_16x16x32_bf16 v[26:29], v[94:97], v[106:109], v[26:29]
	v_mfma_f32_16x16x32_bf16 v[22:25], v[98:101], v[106:109], v[22:25]
	ds_read_b128 v[102:105], v84 offset:4096
	ds_read_b128 v[106:109], v84 offset:6144
	s_waitcnt lgkmcnt(0)
	v_mfma_f32_16x16x32_bf16 v[18:21], v[94:97], v[102:105], v[18:21]
	v_mfma_f32_16x16x32_bf16 v[14:17], v[98:101], v[102:105], v[14:17]
	v_mfma_f32_16x16x32_bf16 v[10:13], v[94:97], v[106:109], v[10:13]
	v_mfma_f32_16x16x32_bf16 v[6:9], v[98:101], v[106:109], v[4:7]

; #define GLDS16(gp, lp) __builtin_amdgcn_global_load_lds((const unsigned*)(gp), (__attribute__((address_space(3))) unsigned*)(lp), 16, 0, 0)
; template <bool SWAP, class Epi, bool THIN = false> ...
;     ...
;     for (int st = 0; st < ns; ++st) {
;       asm volatile("s_waitcnt vmcnt(0)" ::: "memory");
;       __builtin_amdgcn_s_barrier();
;       asm volatile("" ::: "memory");
;       if (st + 1 < ns) {
;         char* nb = smem + ((st + 1) & 1) * 65536;
;         const int ko = (st + 1) * 64;
; #pragma unroll
;         for (int i = 0; i < 4; ++i) { GLDS16(A + (size_t)(ap[i] + ko), nb + tid * 16 + i * 8192); GLDS16(Bt + (size_t)(bp[i] + ko), nb + 32768 + tid * 16 + i * 8192); }
;       }
;       const char* sa = smem + (st & 1) * 65536 + (wr * 64 + fr) * 128;
;       const char* sb = smem + (st & 1) * 65536 + 32768 + (wc * 128 + fr) * 128;
;       if constexpr (THIN) {
;         if (wc == 0) {
; #pragma unroll
;           for (int ks = 0; ks < 2; ++ks) {
;             bf16x8 af[4], bf[2];
; #pragma unroll
;             for (int m = 0; m < 4; ++m) af[m] = *(const bf16x8*)(sa + m * 2048 + (((ks * 4 + fq) ^ swz) << 4));
; #pragma unroll
;             for (int n = 0; n < 2; ++n) bf[n] = *(const bf16x8*)(sb + n * 2048 + (((ks * 4 + fq) ^ swz) << 4));
; #pragma unroll
;             for (int m = 0; m < 4; ++m)
; #pragma unroll
;               for (int n = 0; n < 2; ++n)
;                 acc[m][n] = SWAP ? __builtin_amdgcn_mfma_f32_16x16x32_bf16(bf[n], af[m], acc[m][n], 0, 0, 0)
;                                  : __builtin_amdgcn_mfma_f32_16x16x32_bf16(af[m], bf[n], acc[m][n], 0, 0, 0);
;           }
;         }
.Lthin_ns_4:
	v_readfirstlane_b32 s6, v56
	s_add_i32 m0, s6, 0x0
	v_lshl_add_u64 v[4:5], v[46:47], 0, s[40:41]
	global_load_lds_dwordx4 v[4:5], off
	v_or_b32_e32 v2, 0x180, v38
	s_add_i32 m0, s6, 0x8000
	v_lshl_add_u64 v[4:5], v[2:3], 1, s[18:19]
	global_load_lds_dwordx4 v[4:5], off
	s_add_i32 m0, s6, 0x2000
	v_lshl_add_u64 v[4:5], v[48:49], 0, s[40:41]
	global_load_lds_dwordx4 v[4:5], off
	s_add_i32 m0, s6, 0x4000
	v_lshl_add_u64 v[4:5], v[50:51], 0, s[40:41]
	global_load_lds_dwordx4 v[4:5], off
	s_add_i32 m0, s6, 0x6000
	v_lshl_add_u64 v[4:5], v[52:53], 0, s[40:41]
	global_load_lds_dwordx4 v[4:5], off
	s_and_saveexec_b64 s[6:7], s[4:5]
	s_cbranch_execz .LBB0_1535
	ds_read_b128 v[94:97], v87
	ds_read_b128 v[98:101], v87 offset:2048
	ds_read_b128 v[102:105], v86
	ds_read_b128 v[106:109], v86 offset:2048
	s_waitcnt lgkmcnt(0)
	v_mfma_f32_16x16x32_bf16 v[34:37], v[94:97], v[102:105], v[34:37]
	v_mfma_f32_16x16x32_bf16 v[30:33], v[98:101], v[102:105], v[30:33]
	v_mfma_f32_16x16x32_bf16 v[26:29], v[94:97], v[106:109], v[26:29]
	v_mfma_f32_16x16x32_bf16 v[22:25], v[98:101], v[106:109], v[22:25]
	ds_read_b128 v[102:105], v86 offset:4096
	ds_read_b128 v[106:109], v86 offset:6144
	s_waitcnt lgkmcnt(0)
	v_mfma_f32_16x16x32_bf16 v[18:21], v[94:97], v[102:105], v[18:21]
	v_mfma_f32_16x16x32_bf16 v[10:13], v[94:97], v[106:109], v[10:13]
	ds_read_b128 v[94:97], v89
	v_mfma_f32_16x16x32_bf16 v[14:17], v[98:101], v[102:105], v[14:17]
	v_mfma_f32_16x16x32_bf16 v[4:7], v[98:101], v[106:109], v[6:9]
	ds_read_b128 v[98:101], v89 offset:2048
	ds_read_b128 v[102:105], v88
	ds_read_b128 v[106:109], v88 offset:2048
	s_waitcnt lgkmcnt(0)
	v_mfma_f32_16x16x32_bf16 v[34:37], v[94:97], v[102:105], v[34:37]
	v_mfma_f32_16x16x32_bf16 v[30:33], v[98:101], v[102:105], v[30:33]
	v_mfma_f32_16x16x32_bf16 v[26:29], v[94:97], v[106:109], v[26:29]
	v_mfma_f32_16x16x32_bf16 v[22:25], v[98:101], v[106:109], v[22:25]
	ds_read_b128 v[102:105], v88 offset:4096
	ds_read_b128 v[106:109], v88 offset:6144
	s_waitcnt lgkmcnt(0)
	v_mfma_f32_16x16x32_bf16 v[18:21], v[94:97], v[102:105], v[18:21]
	v_mfma_f32_16x16x32_bf16 v[14:17], v[98:101], v[102:105], v[14:17]
	v_mfma_f32_16x16x32_bf16 v[10:13], v[94:97], v[106:109], v[10:13]
	v_mfma_f32_16x16x32_bf16 v[6:9], v[98:101], v[106:109], v[4:7]

; #define GLDS16(gp, lp) __builtin_amdgcn_global_load_lds((const unsigned*)(gp), (__attribute__((address_space(3))) unsigned*)(lp), 16, 0, 0)
; template <bool SWAP, class Epi, bool THIN = false> ...
;     ...
;     for (int st = 0; st < ns; ++st) {
;       asm volatile("s_waitcnt vmcnt(0)" ::: "memory");
;       __builtin_amdgcn_s_barrier();
;       asm volatile("" ::: "memory");
;       if (st + 1 < ns) {
;         char* nb = smem + ((st + 1) & 1) * 65536;
;         const int ko = (st + 1) * 64;
; #pragma unroll
;         for (int i = 0; i < 4; ++i) { GLDS16(A + (size_t)(ap[i] + ko), nb + tid * 16 + i * 8192); GLDS16(Bt + (size_t)(bp[i] + ko), nb + 32768 + tid * 16 + i * 8192); }
;       }
;       const char* sa = smem + (st & 1) * 65536 + (wr * 64 + fr) * 128;
;       const char* sb = smem + (st & 1) * 65536 + 32768 + (wc * 128 + fr) * 128;
;       if constexpr (THIN) {
;         if (wc == 0) {
; #pragma unroll
;           for (int ks = 0; ks < 2; ++ks) {
;             bf16x8 af[4], bf[2];
; #pragma unroll
;             for (int m = 0; m < 4; ++m) af[m] = *(const bf16x8*)(sa + m * 2048 + (((ks * 4 + fq) ^ swz) << 4));
; #pragma unroll
;             for (int n = 0; n < 2; ++n) bf[n] = *(const bf16x8*)(sb + n * 2048 + (((ks * 4 + fq) ^ swz) << 4));
; #pragma unroll
;             for (int m = 0; m < 4; ++m)
; #pragma unroll
;               for (int n = 0; n < 2; ++n)
;                 acc[m][n] = SWAP ? __builtin_amdgcn_mfma_f32_16x16x32_bf16(bf[n], af[m], acc[m][n], 0, 0, 0)
;                                  : __builtin_amdgcn_mfma_f32_16x16x32_bf16(af[m], bf[n], acc[m][n], 0, 0, 0);
;           }
;         }
.Lthin_ns_5:
	v_readfirstlane_b32 s6, v56
	s_add_i32 m0, s6, 0x10000
	v_lshl_add_u64 v[4:5], v[46:47], 0, s[42:43]
	global_load_lds_dwordx4 v[4:5], off
	v_or_b32_e32 v2, 0x1c0, v38
	s_add_i32 m0, s6, 0x18000
	v_lshl_add_u64 v[4:5], v[2:3], 1, s[18:19]
	global_load_lds_dwordx4 v[4:5], off
	s_add_i32 m0, s6, 0x12000
	v_lshl_add_u64 v[4:5], v[48:49], 0, s[42:43]
	global_load_lds_dwordx4 v[4:5], off
	s_add_i32 m0, s6, 0x14000
	v_lshl_add_u64 v[4:5], v[50:51], 0, s[42:43]
	global_load_lds_dwordx4 v[4:5], off
	s_add_i32 m0, s6, 0x16000
	v_lshl_add_u64 v[4:5], v[52:53], 0, s[42:43]
	global_load_lds_dwordx4 v[4:5], off
	s_and_saveexec_b64 s[6:7], s[4:5]
	s_cbranch_execz .LBB0_1537
	ds_read_b128 v[94:97], v119 offset:32768
	ds_read_b128 v[98:101], v119 offset:34816
	ds_read_b128 v[102:105], v118
	ds_read_b128 v[106:109], v118 offset:2048
	s_waitcnt lgkmcnt(0)
	v_mfma_f32_16x16x32_bf16 v[34:37], v[94:97], v[102:105], v[34:37]
	v_mfma_f32_16x16x32_bf16 v[30:33], v[98:101], v[102:105], v[30:33]
	v_mfma_f32_16x16x32_bf16 v[26:29], v[94:97], v[106:109], v[26:29]
	v_mfma_f32_16x16x32_bf16 v[22:25], v[98:101], v[106:109], v[22:25]
	ds_read_b128 v[102:105], v118 offset:4096
	ds_read_b128 v[106:109], v118 offset:6144
	s_waitcnt lgkmcnt(0)
	v_mfma_f32_16x16x32_bf16 v[18:21], v[94:97], v[102:105], v[18:21]
	v_mfma_f32_16x16x32_bf16 v[10:13], v[94:97], v[106:109], v[10:13]
	ds_read_b128 v[94:97], v121 offset:32768
	v_mfma_f32_16x16x32_bf16 v[14:17], v[98:101], v[102:105], v[14:17]
	v_mfma_f32_16x16x32_bf16 v[4:7], v[98:101], v[106:109], v[6:9]
	ds_read_b128 v[98:101], v121 offset:34816
	ds_read_b128 v[102:105], v120
	ds_read_b128 v[106:109], v120 offset:2048
	s_waitcnt lgkmcnt(0)
	v_mfma_f32_16x16x32_bf16 v[34:37], v[94:97], v[102:105], v[34:37]
	v_mfma_f32_16x16x32_bf16 v[30:33], v[98:101], v[102:105], v[30:33]
	v_mfma_f32_16x16x32_bf16 v[26:29], v[94:97], v[106:109], v[26:29]
	v_mfma_f32_16x16x32_bf16 v[22:25], v[98:101], v[106:109], v[22:25]
	ds_read_b128 v[102:105], v120 offset:4096
	ds_read_b128 v[106:109], v120 offset:6144
	s_waitcnt lgkmcnt(0)
	v_mfma_f32_16x16x32_bf16 v[18:21], v[94:97], v[102:105], v[18:21]
	v_mfma_f32_16x16x32_bf16 v[14:17], v[98:101], v[102:105], v[14:17]
	v_mfma_f32_16x16x32_bf16 v[10:13], v[94:97], v[106:109], v[10:13]
	v_mfma_f32_16x16x32_bf16 v[6:9], v[98:101], v[106:109], v[4:7]

; #define GLDS16(gp, lp) __builtin_amdgcn_global_load_lds((const unsigned*)(gp), (__attribute__((address_space(3))) unsigned*)(lp), 16, 0, 0)
; template <bool SWAP, class Epi, bool THIN = false> ...
;     ...
;     for (int st = 0; st < ns; ++st) {
;       asm volatile("s_waitcnt vmcnt(0)" ::: "memory");
;       __builtin_amdgcn_s_barrier();
;       asm volatile("" ::: "memory");
;       if (st + 1 < ns) {
;         char* nb = smem + ((st + 1) & 1) * 65536;
;         const int ko = (st + 1) * 64;
; #pragma unroll
;         for (int i = 0; i < 4; ++i) { GLDS16(A + (size_t)(ap[i] + ko), nb + tid * 16 + i * 8192); GLDS16(Bt + (size_t)(bp[i] + ko), nb + 32768 + tid * 16 + i * 8192); }
;       }
;       const char* sa = smem + (st & 1) * 65536 + (wr * 64 + fr) * 128;
;       const char* sb = smem + (st & 1) * 65536 + 32768 + (wc * 128 + fr) * 128;
;       if constexpr (THIN) {
;         if (wc == 0) {
; #pragma unroll
;           for (int ks = 0; ks < 2; ++ks) {
;             bf16x8 af[4], bf[2];
; #pragma unroll
;             for (int m = 0; m < 4; ++m) af[m] = *(const bf16x8*)(sa + m * 2048 + (((ks * 4 + fq) ^ swz) << 4));
; #pragma unroll
;             for (int n = 0; n < 2; ++n) bf[n] = *(const bf16x8*)(sb + n * 2048 + (((ks * 4 + fq) ^ swz) << 4));
; #pragma unroll
;             for (int m = 0; m < 4; ++m)
; #pragma unroll
;               for (int n = 0; n < 2; ++n)
;                 acc[m][n] = SWAP ? __builtin_amdgcn_mfma_f32_16x16x32_bf16(bf[n], af[m], acc[m][n], 0, 0, 0)
;                                  : __builtin_amdgcn_mfma_f32_16x16x32_bf16(af[m], bf[n], acc[m][n], 0, 0, 0);
;           }
;         }
.Lthin_ns_6:
	v_readfirstlane_b32 s6, v56
	s_add_i32 m0, s6, 0x1a000
	v_lshl_add_u64 v[4:5], v[46:47], 0, s[44:45]
	global_load_lds_dwordx4 v[4:5], off
	v_or_b32_e32 v2, 0x200, v38
	s_add_i32 m0, s6, 0x22000
	v_lshl_add_u64 v[4:5], v[2:3], 1, s[18:19]
	global_load_lds_dwordx4 v[4:5], off
	s_add_i32 m0, s6, 0x1c000
	v_lshl_add_u64 v[4:5], v[48:49], 0, s[44:45]
	global_load_lds_dwordx4 v[4:5], off
	s_add_i32 m0, s6, 0x1e000
	v_lshl_add_u64 v[4:5], v[50:51], 0, s[44:45]
	global_load_lds_dwordx4 v[4:5], off
	s_add_i32 m0, s6, 0x20000
	v_lshl_add_u64 v[4:5], v[52:53], 0, s[44:45]
	global_load_lds_dwordx4 v[4:5], off
	s_and_saveexec_b64 s[6:7], s[4:5]
	s_cbranch_execz .LBB0_1539
	ds_read_b128 v[94:97], v83 offset:32768
	ds_read_b128 v[98:101], v83 offset:34816
	ds_read_b128 v[102:105], v82
	ds_read_b128 v[106:109], v82 offset:2048
	s_waitcnt lgkmcnt(0)
	v_mfma_f32_16x16x32_bf16 v[34:37], v[94:97], v[102:105], v[34:37]
	v_mfma_f32_16x16x32_bf16 v[30:33], v[98:101], v[102:105], v[30:33]
	v_mfma_f32_16x16x32_bf16 v[26:29], v[94:97], v[106:109], v[26:29]
	v_mfma_f32_16x16x32_bf16 v[22:25], v[98:101], v[106:109], v[22:25]
	ds_read_b128 v[102:105], v82 offset:4096
	ds_read_b128 v[106:109], v82 offset:6144
	s_waitcnt lgkmcnt(0)
	v_mfma_f32_16x16x32_bf16 v[18:21], v[94:97], v[102:105], v[18:21]
	v_mfma_f32_16x16x32_bf16 v[10:13], v[94:97], v[106:109], v[10:13]
	ds_read_b128 v[94:97], v85 offset:32768
	v_mfma_f32_16x16x32_bf16 v[14:17], v[98:101], v[102:105], v[14:17]
	v_mfma_f32_16x16x32_bf16 v[4:7], v[98:101], v[106:109], v[6:9]
	ds_read_b128 v[98:101], v85 offset:34816
	ds_read_b128 v[102:105], v84
	ds_read_b128 v[106:109], v84 offset:2048
	s_waitcnt lgkmcnt(0)
	v_mfma_f32_16x16x32_bf16 v[34:37], v[94:97], v[102:105], v[34:37]
	v_mfma_f32_16x16x32_bf16 v[30:33], v[98:101], v[102:105], v[30:33]
	v_mfma_f32_16x16x32_bf16 v[26:29], v[94:97], v[106:109], v[26:29]
	v_mfma_f32_16x16x32_bf16 v[22:25], v[98:101], v[106:109], v[22:25]
	ds_read_b128 v[102:105], v84 offset:4096
	ds_read_b128 v[106:109], v84 offset:6144
	s_waitcnt lgkmcnt(0)
	v_mfma_f32_16x16x32_bf16 v[18:21], v[94:97], v[102:105], v[18:21]
	v_mfma_f32_16x16x32_bf16 v[14:17], v[98:101], v[102:105], v[14:17]
	v_mfma_f32_16x16x32_bf16 v[10:13], v[94:97], v[106:109], v[10:13]
	v_mfma_f32_16x16x32_bf16 v[6:9], v[98:101], v[106:109], v[4:7]

; #define GLDS16(gp, lp) __builtin_amdgcn_global_load_lds((const unsigned*)(gp), (__attribute__((address_space(3))) unsigned*)(lp), 16, 0, 0)
; template <bool SWAP, class Epi, bool THIN = false> ...
;     ...
;     for (int st = 0; st < ns; ++st) {
;       asm volatile("s_waitcnt vmcnt(0)" ::: "memory");
;       __builtin_amdgcn_s_barrier();
;       asm volatile("" ::: "memory");
;       if (st + 1 < ns) {
;         char* nb = smem + ((st + 1) & 1) * 65536;
;         const int ko = (st + 1) * 64;
; #pragma unroll
;         for (int i = 0; i < 4; ++i) { GLDS16(A + (size_t)(ap[i] + ko), nb + tid * 16 + i * 8192); GLDS16(Bt + (size_t)(bp[i] + ko), nb + 32768 + tid * 16 + i * 8192); }
;       }
;       const char* sa = smem + (st & 1) * 65536 + (wr * 64 + fr) * 128;
;       const char* sb = smem + (st & 1) * 65536 + 32768 + (wc * 128 + fr) * 128;
;       if constexpr (THIN) {
;         if (wc == 0) {
; #pragma unroll
;           for (int ks = 0; ks < 2; ++ks) {
;             bf16x8 af[4], bf[2];
; #pragma unroll
;             for (int m = 0; m < 4; ++m) af[m] = *(const bf16x8*)(sa + m * 2048 + (((ks * 4 + fq) ^ swz) << 4));
; #pragma unroll
;             for (int n = 0; n < 2; ++n) bf[n] = *(const bf16x8*)(sb + n * 2048 + (((ks * 4 + fq) ^ swz) << 4));
; #pragma unroll
;             for (int m = 0; m < 4; ++m)
; #pragma unroll
;               for (int n = 0; n < 2; ++n)
;                 acc[m][n] = SWAP ? __builtin_amdgcn_mfma_f32_16x16x32_bf16(bf[n], af[m], acc[m][n], 0, 0, 0)
;                                  : __builtin_amdgcn_mfma_f32_16x16x32_bf16(af[m], bf[n], acc[m][n], 0, 0, 0);
;           }
;         }
.Lthin_ns_7:
	v_readfirstlane_b32 s6, v56
	s_add_i32 m0, s6, 0x0
	v_lshl_add_u64 v[4:5], v[46:47], 0, s[48:49]
	global_load_lds_dwordx4 v[4:5], off
	v_or_b32_e32 v2, 0x240, v38
	s_add_i32 m0, s6, 0x8000
	v_lshl_add_u64 v[4:5], v[2:3], 1, s[18:19]
	global_load_lds_dwordx4 v[4:5], off
	s_add_i32 m0, s6, 0x2000
	v_lshl_add_u64 v[4:5], v[48:49], 0, s[48:49]
	global_load_lds_dwordx4 v[4:5], off
	s_add_i32 m0, s6, 0x4000
	v_lshl_add_u64 v[4:5], v[50:51], 0, s[48:49]
	global_load_lds_dwordx4 v[4:5], off
	s_add_i32 m0, s6, 0x6000
	v_lshl_add_u64 v[4:5], v[52:53], 0, s[48:49]
	global_load_lds_dwordx4 v[4:5], off
	s_and_saveexec_b64 s[6:7], s[4:5]
	s_cbranch_execz .LBB0_1541
	ds_read_b128 v[94:97], v87
	ds_read_b128 v[98:101], v87 offset:2048
	ds_read_b128 v[102:105], v86
	ds_read_b128 v[106:109], v86 offset:2048
	s_waitcnt lgkmcnt(0)
	v_mfma_f32_16x16x32_bf16 v[34:37], v[94:97], v[102:105], v[34:37]
	v_mfma_f32_16x16x32_bf16 v[30:33], v[98:101], v[102:105], v[30:33]
	v_mfma_f32_16x16x32_bf16 v[26:29], v[94:97], v[106:109], v[26:29]
	v_mfma_f32_16x16x32_bf16 v[22:25], v[98:101], v[106:109], v[22:25]
	ds_read_b128 v[102:105], v86 offset:4096
	ds_read_b128 v[106:109], v86 offset:6144
	s_waitcnt lgkmcnt(0)
	v_mfma_f32_16x16x32_bf16 v[18:21], v[94:97], v[102:105], v[18:21]
	v_mfma_f32_16x16x32_bf16 v[10:13], v[94:97], v[106:109], v[10:13]
	ds_read_b128 v[94:97], v89
	v_mfma_f32_16x16x32_bf16 v[14:17], v[98:101], v[102:105], v[14:17]
	v_mfma_f32_16x16x32_bf16 v[4:7], v[98:101], v[106:109], v[6:9]
	ds_read_b128 v[98:101], v89 offset:2048
	ds_read_b128 v[102:105], v88
	ds_read_b128 v[106:109], v88 offset:2048
	s_waitcnt lgkmcnt(0)
	v_mfma_f32_16x16x32_bf16 v[34:37], v[94:97], v[102:105], v[34:37]
	v_mfma_f32_16x16x32_bf16 v[30:33], v[98:101], v[102:105], v[30:33]
	v_mfma_f32_16x16x32_bf16 v[26:29], v[94:97], v[106:109], v[26:29]
	v_mfma_f32_16x16x32_bf16 v[22:25], v[98:101], v[106:109], v[22:25]
	ds_read_b128 v[102:105], v88 offset:4096
	ds_read_b128 v[106:109], v88 offset:6144
	s_waitcnt lgkmcnt(0)
	v_mfma_f32_16x16x32_bf16 v[18:21], v[94:97], v[102:105], v[18:21]
	v_mfma_f32_16x16x32_bf16 v[14:17], v[98:101], v[102:105], v[14:17]
	v_mfma_f32_16x16x32_bf16 v[10:13], v[94:97], v[106:109], v[10:13]
	v_mfma_f32_16x16x32_bf16 v[6:9], v[98:101], v[106:109], v[4:7]

; #define GLDS16(gp, lp) __builtin_amdgcn_global_load_lds((const unsigned*)(gp), (__attribute__((address_space(3))) unsigned*)(lp), 16, 0, 0)
; template <bool SWAP, class Epi, bool THIN = false> ...
;     ...
;     for (int st = 0; st < ns; ++st) {
;       asm volatile("s_waitcnt vmcnt(0)" ::: "memory");
;       __builtin_amdgcn_s_barrier();
;       asm volatile("" ::: "memory");
;       if (st + 1 < ns) {
;         char* nb = smem + ((st + 1) & 1) * 65536;
;         const int ko = (st + 1) * 64;
; #pragma unroll
;         for (int i = 0; i < 4; ++i) { GLDS16(A + (size_t)(ap[i] + ko), nb + tid * 16 + i * 8192); GLDS16(Bt + (size_t)(bp[i] + ko), nb + 32768 + tid * 16 + i * 8192); }
;       }
;       const char* sa = smem + (st & 1) * 65536 + (wr * 64 + fr) * 128;
;       const char* sb = smem + (st & 1) * 65536 + 32768 + (wc * 128 + fr) * 128;
;       if constexpr (THIN) {
;         if (wc == 0) {
; #pragma unroll
;           for (int ks = 0; ks < 2; ++ks) {
;             bf16x8 af[4], bf[2];
; #pragma unroll
;             for (int m = 0; m < 4; ++m) af[m] = *(const bf16x8*)(sa + m * 2048 + (((ks * 4 + fq) ^ swz) << 4));
; #pragma unroll
;             for (int n = 0; n < 2; ++n) bf[n] = *(const bf16x8*)(sb + n * 2048 + (((ks * 4 + fq) ^ swz) << 4));
; #pragma unroll
;             for (int m = 0; m < 4; ++m)
; #pragma unroll
;               for (int n = 0; n < 2; ++n)
;                 acc[m][n] = SWAP ? __builtin_amdgcn_mfma_f32_16x16x32_bf16(bf[n], af[m], acc[m][n], 0, 0, 0)
;                                  : __builtin_amdgcn_mfma_f32_16x16x32_bf16(af[m], bf[n], acc[m][n], 0, 0, 0);
;           }
;         }
.Lthin_ns_8:
	v_readfirstlane_b32 s6, v56
	s_add_i32 m0, s6, 0x10000
	v_lshl_add_u64 v[4:5], v[46:47], 0, s[50:51]
	global_load_lds_dwordx4 v[4:5], off
	v_or_b32_e32 v2, 0x280, v38
	s_add_i32 m0, s6, 0x18000
	v_lshl_add_u64 v[4:5], v[2:3], 1, s[18:19]
	global_load_lds_dwordx4 v[4:5], off
	s_add_i32 m0, s6, 0x12000
	v_lshl_add_u64 v[4:5], v[48:49], 0, s[50:51]
	global_load_lds_dwordx4 v[4:5], off
	s_add_i32 m0, s6, 0x14000
	v_lshl_add_u64 v[4:5], v[50:51], 0, s[50:51]
	global_load_lds_dwordx4 v[4:5], off
	s_add_i32 m0, s6, 0x16000
	v_lshl_add_u64 v[4:5], v[52:53], 0, s[50:51]
	global_load_lds_dwordx4 v[4:5], off
	s_and_saveexec_b64 s[6:7], s[4:5]
	s_cbranch_execz .LBB0_1543
	ds_read_b128 v[94:97], v119 offset:32768
	ds_read_b128 v[98:101], v119 offset:34816
	ds_read_b128 v[102:105], v118
	ds_read_b128 v[106:109], v118 offset:2048
	s_waitcnt lgkmcnt(0)
	v_mfma_f32_16x16x32_bf16 v[34:37], v[94:97], v[102:105], v[34:37]
	v_mfma_f32_16x16x32_bf16 v[30:33], v[98:101], v[102:105], v[30:33]
	v_mfma_f32_16x16x32_bf16 v[26:29], v[94:97], v[106:109], v[26:29]
	v_mfma_f32_16x16x32_bf16 v[22:25], v[98:101], v[106:109], v[22:25]
	ds_read_b128 v[102:105], v118 offset:4096
	ds_read_b128 v[106:109], v118 offset:6144
	s_waitcnt lgkmcnt(0)
	v_mfma_f32_16x16x32_bf16 v[18:21], v[94:97], v[102:105], v[18:21]
	v_mfma_f32_16x16x32_bf16 v[10:13], v[94:97], v[106:109], v[10:13]
	ds_read_b128 v[94:97], v121 offset:32768
	v_mfma_f32_16x16x32_bf16 v[14:17], v[98:101], v[102:105], v[14:17]
	v_mfma_f32_16x16x32_bf16 v[4:7], v[98:101], v[106:109], v[6:9]
	ds_read_b128 v[98:101], v121 offset:34816
	ds_read_b128 v[102:105], v120
	ds_read_b128 v[106:109], v120 offset:2048
	s_waitcnt lgkmcnt(0)
	v_mfma_f32_16x16x32_bf16 v[34:37], v[94:97], v[102:105], v[34:37]
	v_mfma_f32_16x16x32_bf16 v[30:33], v[98:101], v[102:105], v[30:33]
	v_mfma_f32_16x16x32_bf16 v[26:29], v[94:97], v[106:109], v[26:29]
	v_mfma_f32_16x16x32_bf16 v[22:25], v[98:101], v[106:109], v[22:25]
	ds_read_b128 v[102:105], v120 offset:4096
	ds_read_b128 v[106:109], v120 offset:6144
	s_waitcnt lgkmcnt(0)
	v_mfma_f32_16x16x32_bf16 v[18:21], v[94:97], v[102:105], v[18:21]
	v_mfma_f32_16x16x32_bf16 v[14:17], v[98:101], v[102:105], v[14:17]
	v_mfma_f32_16x16x32_bf16 v[10:13], v[94:97], v[106:109], v[10:13]
	v_mfma_f32_16x16x32_bf16 v[6:9], v[98:101], v[106:109], v[4:7]

; #define GLDS16(gp, lp) __builtin_amdgcn_global_load_lds((const unsigned*)(gp), (__attribute__((address_space(3))) unsigned*)(lp), 16, 0, 0)
; template <bool SWAP, class Epi, bool THIN = false> ...
;     ...
;     for (int st = 0; st < ns; ++st) {
;       asm volatile("s_waitcnt vmcnt(0)" ::: "memory");
;       __builtin_amdgcn_s_barrier();
;       asm volatile("" ::: "memory");
;       if (st + 1 < ns) {
;         char* nb = smem + ((st + 1) & 1) * 65536;
;         const int ko = (st + 1) * 64;
; #pragma unroll
;         for (int i = 0; i < 4; ++i) { GLDS16(A + (size_t)(ap[i] + ko), nb + tid * 16 + i * 8192); GLDS16(Bt + (size_t)(bp[i] + ko), nb + 32768 + tid * 16 + i * 8192); }
;       }
;       const char* sa = smem + (st & 1) * 65536 + (wr * 64 + fr) * 128;
;       const char* sb = smem + (st & 1) * 65536 + 32768 + (wc * 128 + fr) * 128;
;       if constexpr (THIN) {
;         if (wc == 0) {
; #pragma unroll
;           for (int ks = 0; ks < 2; ++ks) {
;             bf16x8 af[4], bf[2];
; #pragma unroll
;             for (int m = 0; m < 4; ++m) af[m] = *(const bf16x8*)(sa + m * 2048 + (((ks * 4 + fq) ^ swz) << 4));
; #pragma unroll
;             for (int n = 0; n < 2; ++n) bf[n] = *(const bf16x8*)(sb + n * 2048 + (((ks * 4 + fq) ^ swz) << 4));
; #pragma unroll
;             for (int m = 0; m < 4; ++m)
; #pragma unroll
;               for (int n = 0; n < 2; ++n)
;                 acc[m][n] = SWAP ? __builtin_amdgcn_mfma_f32_16x16x32_bf16(bf[n], af[m], acc[m][n], 0, 0, 0)
;                                  : __builtin_amdgcn_mfma_f32_16x16x32_bf16(af[m], bf[n], acc[m][n], 0, 0, 0);
;           }
;         }
.Lthin_ns_9:
	v_readfirstlane_b32 s6, v56
	s_add_i32 m0, s6, 0x1a000
	v_lshl_add_u64 v[4:5], v[46:47], 0, s[56:57]
	global_load_lds_dwordx4 v[4:5], off
	v_or_b32_e32 v2, 0x2c0, v38
	s_add_i32 m0, s6, 0x22000
	v_lshl_add_u64 v[4:5], v[2:3], 1, s[18:19]
	global_load_lds_dwordx4 v[4:5], off
	s_add_i32 m0, s6, 0x1c000
	v_lshl_add_u64 v[4:5], v[48:49], 0, s[56:57]
	global_load_lds_dwordx4 v[4:5], off
	s_add_i32 m0, s6, 0x1e000
	v_lshl_add_u64 v[4:5], v[50:51], 0, s[56:57]
	global_load_lds_dwordx4 v[4:5], off
	s_add_i32 m0, s6, 0x20000
	v_lshl_add_u64 v[4:5], v[52:53], 0, s[56:57]
	global_load_lds_dwordx4 v[4:5], off
	s_and_saveexec_b64 s[6:7], s[4:5]
	s_cbranch_execz .LBB0_1545
	ds_read_b128 v[94:97], v83 offset:32768
	ds_read_b128 v[98:101], v83 offset:34816
	ds_read_b128 v[102:105], v82
	ds_read_b128 v[106:109], v82 offset:2048
	s_waitcnt lgkmcnt(0)
	v_mfma_f32_16x16x32_bf16 v[34:37], v[94:97], v[102:105], v[34:37]
	v_mfma_f32_16x16x32_bf16 v[30:33], v[98:101], v[102:105], v[30:33]
	v_mfma_f32_16x16x32_bf16 v[26:29], v[94:97], v[106:109], v[26:29]
	v_mfma_f32_16x16x32_bf16 v[22:25], v[98:101], v[106:109], v[22:25]
	ds_read_b128 v[102:105], v82 offset:4096
	ds_read_b128 v[106:109], v82 offset:6144
	s_waitcnt lgkmcnt(0)
	v_mfma_f32_16x16x32_bf16 v[18:21], v[94:97], v[102:105], v[18:21]
	v_mfma_f32_16x16x32_bf16 v[10:13], v[94:97], v[106:109], v[10:13]
	ds_read_b128 v[94:97], v85 offset:32768
	v_mfma_f32_16x16x32_bf16 v[14:17], v[98:101], v[102:105], v[14:17]
	v_mfma_f32_16x16x32_bf16 v[4:7], v[98:101], v[106:109], v[6:9]
	ds_read_b128 v[98:101], v85 offset:34816
	ds_read_b128 v[102:105], v84
	ds_read_b128 v[106:109], v84 offset:2048
	s_waitcnt lgkmcnt(0)
	v_mfma_f32_16x16x32_bf16 v[34:37], v[94:97], v[102:105], v[34:37]
	v_mfma_f32_16x16x32_bf16 v[30:33], v[98:101], v[102:105], v[30:33]
	v_mfma_f32_16x16x32_bf16 v[26:29], v[94:97], v[106:109], v[26:29]
	v_mfma_f32_16x16x32_bf16 v[22:25], v[98:101], v[106:109], v[22:25]
	ds_read_b128 v[102:105], v84 offset:4096
	ds_read_b128 v[106:109], v84 offset:6144
	s_waitcnt lgkmcnt(0)
	v_mfma_f32_16x16x32_bf16 v[18:21], v[94:97], v[102:105], v[18:21]
	v_mfma_f32_16x16x32_bf16 v[14:17], v[98:101], v[102:105], v[14:17]
	v_mfma_f32_16x16x32_bf16 v[10:13], v[94:97], v[106:109], v[10:13]
	v_mfma_f32_16x16x32_bf16 v[6:9], v[98:101], v[106:109], v[4:7]

; #define GLDS16(gp, lp) __builtin_amdgcn_global_load_lds((const unsigned*)(gp), (__attribute__((address_space(3))) unsigned*)(lp), 16, 0, 0)
; template <bool SWAP, class Epi, bool THIN = false> ...
;     ...
;     for (int st = 0; st < ns; ++st) {
;       asm volatile("s_waitcnt vmcnt(0)" ::: "memory");
;       __builtin_amdgcn_s_barrier();
;       asm volatile("" ::: "memory");
;       if (st + 1 < ns) {
;         char* nb = smem + ((st + 1) & 1) * 65536;
;         const int ko = (st + 1) * 64;
; #pragma unroll
;         for (int i = 0; i < 4; ++i) { GLDS16(A + (size_t)(ap[i] + ko), nb + tid * 16 + i * 8192); GLDS16(Bt + (size_t)(bp[i] + ko), nb + 32768 + tid * 16 + i * 8192); }
;       }
;       const char* sa = smem + (st & 1) * 65536 + (wr * 64 + fr) * 128;
;       const char* sb = smem + (st & 1) * 65536 + 32768 + (wc * 128 + fr) * 128;
;       if constexpr (THIN) {
;         if (wc == 0) {
; #pragma unroll
;           for (int ks = 0; ks < 2; ++ks) {
;             bf16x8 af[4], bf[2];
; #pragma unroll
;             for (int m = 0; m < 4; ++m) af[m] = *(const bf16x8*)(sa + m * 2048 + (((ks * 4 + fq) ^ swz) << 4));
; #pragma unroll
;             for (int n = 0; n < 2; ++n) bf[n] = *(const bf16x8*)(sb + n * 2048 + (((ks * 4 + fq) ^ swz) << 4));
; #pragma unroll
;             for (int m = 0; m < 4; ++m)
; #pragma unroll
;               for (int n = 0; n < 2; ++n)
;                 acc[m][n] = SWAP ? __builtin_amdgcn_mfma_f32_16x16x32_bf16(bf[n], af[m], acc[m][n], 0, 0, 0)
;                                  : __builtin_amdgcn_mfma_f32_16x16x32_bf16(af[m], bf[n], acc[m][n], 0, 0, 0);
;           }
;         }
.Lthin_ns_10:
	v_readfirstlane_b32 s6, v56
	s_add_i32 m0, s6, 0x0
	v_lshl_add_u64 v[4:5], v[46:47], 0, s[58:59]
	global_load_lds_dwordx4 v[4:5], off
	v_or_b32_e32 v2, 0x300, v38
	s_add_i32 m0, s6, 0x8000
	v_lshl_add_u64 v[4:5], v[2:3], 1, s[18:19]
	global_load_lds_dwordx4 v[4:5], off
	s_add_i32 m0, s6, 0x2000
	v_lshl_add_u64 v[4:5], v[48:49], 0, s[58:59]
	global_load_lds_dwordx4 v[4:5], off
	s_add_i32 m0, s6, 0x4000
	v_lshl_add_u64 v[4:5], v[50:51], 0, s[58:59]
	global_load_lds_dwordx4 v[4:5], off
	s_add_i32 m0, s6, 0x6000
	v_lshl_add_u64 v[4:5], v[52:53], 0, s[58:59]
	global_load_lds_dwordx4 v[4:5], off
	s_and_saveexec_b64 s[6:7], s[4:5]
	s_cbranch_execz .LBB0_1547
	ds_read_b128 v[94:97], v87
	ds_read_b128 v[98:101], v87 offset:2048
	ds_read_b128 v[102:105], v86
	ds_read_b128 v[106:109], v86 offset:2048
	s_waitcnt lgkmcnt(0)
	v_mfma_f32_16x16x32_bf16 v[34:37], v[94:97], v[102:105], v[34:37]
	v_mfma_f32_16x16x32_bf16 v[30:33], v[98:101], v[102:105], v[30:33]
	v_mfma_f32_16x16x32_bf16 v[26:29], v[94:97], v[106:109], v[26:29]
	v_mfma_f32_16x16x32_bf16 v[22:25], v[98:101], v[106:109], v[22:25]
	ds_read_b128 v[102:105], v86 offset:4096
	ds_read_b128 v[106:109], v86 offset:6144
	s_waitcnt lgkmcnt(0)
	v_mfma_f32_16x16x32_bf16 v[18:21], v[94:97], v[102:105], v[18:21]
	v_mfma_f32_16x16x32_bf16 v[10:13], v[94:97], v[106:109], v[10:13]
	ds_read_b128 v[94:97], v89
	v_mfma_f32_16x16x32_bf16 v[14:17], v[98:101], v[102:105], v[14:17]
	v_mfma_f32_16x16x32_bf16 v[4:7], v[98:101], v[106:109], v[6:9]
	ds_read_b128 v[98:101], v89 offset:2048
	ds_read_b128 v[102:105], v88
	ds_read_b128 v[106:109], v88 offset:2048
	s_waitcnt lgkmcnt(0)
	v_mfma_f32_16x16x32_bf16 v[34:37], v[94:97], v[102:105], v[34:37]
	v_mfma_f32_16x16x32_bf16 v[30:33], v[98:101], v[102:105], v[30:33]
	v_mfma_f32_16x16x32_bf16 v[26:29], v[94:97], v[106:109], v[26:29]
	v_mfma_f32_16x16x32_bf16 v[22:25], v[98:101], v[106:109], v[22:25]
	ds_read_b128 v[102:105], v88 offset:4096
	ds_read_b128 v[106:109], v88 offset:6144
	s_waitcnt lgkmcnt(0)
	v_mfma_f32_16x16x32_bf16 v[18:21], v[94:97], v[102:105], v[18:21]
	v_mfma_f32_16x16x32_bf16 v[14:17], v[98:101], v[102:105], v[14:17]
	v_mfma_f32_16x16x32_bf16 v[10:13], v[94:97], v[106:109], v[10:13]
	v_mfma_f32_16x16x32_bf16 v[6:9], v[98:101], v[106:109], v[4:7]

; #define GLDS16(gp, lp) __builtin_amdgcn_global_load_lds((const unsigned*)(gp), (__attribute__((address_space(3))) unsigned*)(lp), 16, 0, 0)
; template <bool SWAP, class Epi, bool THIN = false> ...
;     ...
;     for (int st = 0; st < ns; ++st) {
;       asm volatile("s_waitcnt vmcnt(0)" ::: "memory");
;       __builtin_amdgcn_s_barrier();
;       asm volatile("" ::: "memory");
;       if (st + 1 < ns) {
;         char* nb = smem + ((st + 1) & 1) * 65536;
;         const int ko = (st + 1) * 64;
; #pragma unroll
;         for (int i = 0; i < 4; ++i) { GLDS16(A + (size_t)(ap[i] + ko), nb + tid * 16 + i * 8192); GLDS16(Bt + (size_t)(bp[i] + ko), nb + 32768 + tid * 16 + i * 8192); }
;       }
;       const char* sa = smem + (st & 1) * 65536 + (wr * 64 + fr) * 128;
;       const char* sb = smem + (st & 1) * 65536 + 32768 + (wc * 128 + fr) * 128;
;       if constexpr (THIN) {
;         if (wc == 0) {
; #pragma unroll
;           for (int ks = 0; ks < 2; ++ks) {
;             bf16x8 af[4], bf[2];
; #pragma unroll
;             for (int m = 0; m < 4; ++m) af[m] = *(const bf16x8*)(sa + m * 2048 + (((ks * 4 + fq) ^ swz) << 4));
; #pragma unroll
;             for (int n = 0; n < 2; ++n) bf[n] = *(const bf16x8*)(sb + n * 2048 + (((ks * 4 + fq) ^ swz) << 4));
; #pragma unroll
;             for (int m = 0; m < 4; ++m)
; #pragma unroll
;               for (int n = 0; n < 2; ++n)
;                 acc[m][n] = SWAP ? __builtin_amdgcn_mfma_f32_16x16x32_bf16(bf[n], af[m], acc[m][n], 0, 0, 0)
;                                  : __builtin_amdgcn_mfma_f32_16x16x32_bf16(af[m], bf[n], acc[m][n], 0, 0, 0);
;           }
;         }
.Lthin_ns_11:
	v_readfirstlane_b32 s6, v56
	s_add_i32 m0, s6, 0x10000
	v_lshl_add_u64 v[4:5], v[46:47], 0, s[60:61]
	global_load_lds_dwordx4 v[4:5], off
	v_or_b32_e32 v2, 0x340, v38
	s_add_i32 m0, s6, 0x18000
	v_lshl_add_u64 v[4:5], v[2:3], 1, s[18:19]
	global_load_lds_dwordx4 v[4:5], off
	s_add_i32 m0, s6, 0x12000
	v_lshl_add_u64 v[4:5], v[48:49], 0, s[60:61]
	global_load_lds_dwordx4 v[4:5], off
	s_add_i32 m0, s6, 0x14000
	v_lshl_add_u64 v[4:5], v[50:51], 0, s[60:61]
	global_load_lds_dwordx4 v[4:5], off
	s_add_i32 m0, s6, 0x16000
	v_lshl_add_u64 v[4:5], v[52:53], 0, s[60:61]
	global_load_lds_dwordx4 v[4:5], off
	s_and_saveexec_b64 s[6:7], s[4:5]
	s_cbranch_execz .LBB0_1549
	ds_read_b128 v[94:97], v119 offset:32768
	ds_read_b128 v[98:101], v119 offset:34816
	ds_read_b128 v[102:105], v118
	ds_read_b128 v[106:109], v118 offset:2048
	s_waitcnt lgkmcnt(0)
	v_mfma_f32_16x16x32_bf16 v[34:37], v[94:97], v[102:105], v[34:37]
	v_mfma_f32_16x16x32_bf16 v[30:33], v[98:101], v[102:105], v[30:33]
	v_mfma_f32_16x16x32_bf16 v[26:29], v[94:97], v[106:109], v[26:29]
	v_mfma_f32_16x16x32_bf16 v[22:25], v[98:101], v[106:109], v[22:25]
	ds_read_b128 v[102:105], v118 offset:4096
	ds_read_b128 v[106:109], v118 offset:6144
	s_waitcnt lgkmcnt(0)
	v_mfma_f32_16x16x32_bf16 v[18:21], v[94:97], v[102:105], v[18:21]
	v_mfma_f32_16x16x32_bf16 v[10:13], v[94:97], v[106:109], v[10:13]
	ds_read_b128 v[94:97], v121 offset:32768
	v_mfma_f32_16x16x32_bf16 v[14:17], v[98:101], v[102:105], v[14:17]
	v_mfma_f32_16x16x32_bf16 v[4:7], v[98:101], v[106:109], v[6:9]
	ds_read_b128 v[98:101], v121 offset:34816
	ds_read_b128 v[102:105], v120
	ds_read_b128 v[106:109], v120 offset:2048
	s_waitcnt lgkmcnt(0)
	v_mfma_f32_16x16x32_bf16 v[34:37], v[94:97], v[102:105], v[34:37]
	v_mfma_f32_16x16x32_bf16 v[30:33], v[98:101], v[102:105], v[30:33]
	v_mfma_f32_16x16x32_bf16 v[26:29], v[94:97], v[106:109], v[26:29]
	v_mfma_f32_16x16x32_bf16 v[22:25], v[98:101], v[106:109], v[22:25]
	ds_read_b128 v[102:105], v120 offset:4096
	ds_read_b128 v[106:109], v120 offset:6144
	s_waitcnt lgkmcnt(0)
	v_mfma_f32_16x16x32_bf16 v[18:21], v[94:97], v[102:105], v[18:21]
	v_mfma_f32_16x16x32_bf16 v[14:17], v[98:101], v[102:105], v[14:17]
	v_mfma_f32_16x16x32_bf16 v[10:13], v[94:97], v[106:109], v[10:13]
	v_mfma_f32_16x16x32_bf16 v[6:9], v[98:101], v[106:109], v[4:7]

; #define GLDS16(gp, lp) __builtin_amdgcn_global_load_lds((const unsigned*)(gp), (__attribute__((address_space(3))) unsigned*)(lp), 16, 0, 0)
; template <bool SWAP, class Epi, bool THIN = false> ...
;     ...
;     for (int st = 0; st < ns; ++st) {
;       asm volatile("s_waitcnt vmcnt(0)" ::: "memory");
;       __builtin_amdgcn_s_barrier();
;       asm volatile("" ::: "memory");
;       if (st + 1 < ns) {
;         char* nb = smem + ((st + 1) & 1) * 65536;
;         const int ko = (st + 1) * 64;
; #pragma unroll
;         for (int i = 0; i < 4; ++i) { GLDS16(A + (size_t)(ap[i] + ko), nb + tid * 16 + i * 8192); GLDS16(Bt + (size_t)(bp[i] + ko), nb + 32768 + tid * 16 + i * 8192); }
;       }
;       const char* sa = smem + (st & 1) * 65536 + (wr * 64 + fr) * 128;
;       const char* sb = smem + (st & 1) * 65536 + 32768 + (wc * 128 + fr) * 128;
;       if constexpr (THIN) {
;         if (wc == 0) {
; #pragma unroll
;           for (int ks = 0; ks < 2; ++ks) {
;             bf16x8 af[4], bf[2];
; #pragma unroll
;             for (int m = 0; m < 4; ++m) af[m] = *(const bf16x8*)(sa + m * 2048 + (((ks * 4 + fq) ^ swz) << 4));
; #pragma unroll
;             for (int n = 0; n < 2; ++n) bf[n] = *(const bf16x8*)(sb + n * 2048 + (((ks * 4 + fq) ^ swz) << 4));
; #pragma unroll
;             for (int m = 0; m < 4; ++m)
; #pragma unroll
;               for (int n = 0; n < 2; ++n)
;                 acc[m][n] = SWAP ? __builtin_amdgcn_mfma_f32_16x16x32_bf16(bf[n], af[m], acc[m][n], 0, 0, 0)
;                                  : __builtin_amdgcn_mfma_f32_16x16x32_bf16(af[m], bf[n], acc[m][n], 0, 0, 0);
;           }
;         }
.Lthin_ns_12:
	v_readfirstlane_b32 s6, v56
	s_add_i32 m0, s6, 0x1a000
	v_lshl_add_u64 v[4:5], v[46:47], 0, s[62:63]
	global_load_lds_dwordx4 v[4:5], off
	v_or_b32_e32 v2, 0x380, v38
	s_add_i32 m0, s6, 0x22000
	v_lshl_add_u64 v[4:5], v[2:3], 1, s[18:19]
	global_load_lds_dwordx4 v[4:5], off
	s_add_i32 m0, s6, 0x1c000
	v_lshl_add_u64 v[4:5], v[48:49], 0, s[62:63]
	global_load_lds_dwordx4 v[4:5], off
	s_add_i32 m0, s6, 0x1e000
	v_lshl_add_u64 v[4:5], v[50:51], 0, s[62:63]
	global_load_lds_dwordx4 v[4:5], off
	s_add_i32 m0, s6, 0x20000
	v_lshl_add_u64 v[4:5], v[52:53], 0, s[62:63]
	global_load_lds_dwordx4 v[4:5], off
	s_and_saveexec_b64 s[6:7], s[4:5]
	s_cbranch_execz .LBB0_1551
	ds_read_b128 v[94:97], v83 offset:32768
	ds_read_b128 v[98:101], v83 offset:34816
	ds_read_b128 v[102:105], v82
	ds_read_b128 v[106:109], v82 offset:2048
	s_waitcnt lgkmcnt(0)
	v_mfma_f32_16x16x32_bf16 v[34:37], v[94:97], v[102:105], v[34:37]
	v_mfma_f32_16x16x32_bf16 v[30:33], v[98:101], v[102:105], v[30:33]
	v_mfma_f32_16x16x32_bf16 v[26:29], v[94:97], v[106:109], v[26:29]
	v_mfma_f32_16x16x32_bf16 v[22:25], v[98:101], v[106:109], v[22:25]
	ds_read_b128 v[102:105], v82 offset:4096
	ds_read_b128 v[106:109], v82 offset:6144
	s_waitcnt lgkmcnt(0)
	v_mfma_f32_16x16x32_bf16 v[18:21], v[94:97], v[102:105], v[18:21]
	v_mfma_f32_16x16x32_bf16 v[10:13], v[94:97], v[106:109], v[10:13]
	ds_read_b128 v[94:97], v85 offset:32768
	v_mfma_f32_16x16x32_bf16 v[14:17], v[98:101], v[102:105], v[14:17]
	v_mfma_f32_16x16x32_bf16 v[4:7], v[98:101], v[106:109], v[6:9]
	ds_read_b128 v[98:101], v85 offset:34816
	ds_read_b128 v[102:105], v84
	ds_read_b128 v[106:109], v84 offset:2048
	s_waitcnt lgkmcnt(0)
	v_mfma_f32_16x16x32_bf16 v[34:37], v[94:97], v[102:105], v[34:37]
	v_mfma_f32_16x16x32_bf16 v[30:33], v[98:101], v[102:105], v[30:33]
	v_mfma_f32_16x16x32_bf16 v[26:29], v[94:97], v[106:109], v[26:29]
	v_mfma_f32_16x16x32_bf16 v[22:25], v[98:101], v[106:109], v[22:25]
	ds_read_b128 v[102:105], v84 offset:4096
	ds_read_b128 v[106:109], v84 offset:6144
	s_waitcnt lgkmcnt(0)
	v_mfma_f32_16x16x32_bf16 v[18:21], v[94:97], v[102:105], v[18:21]
	v_mfma_f32_16x16x32_bf16 v[14:17], v[98:101], v[102:105], v[14:17]
	v_mfma_f32_16x16x32_bf16 v[10:13], v[94:97], v[106:109], v[10:13]
	v_mfma_f32_16x16x32_bf16 v[6:9], v[98:101], v[106:109], v[4:7]

; #define GLDS16(gp, lp) __builtin_amdgcn_global_load_lds((const unsigned*)(gp), (__attribute__((address_space(3))) unsigned*)(lp), 16, 0, 0)
; template <bool SWAP, class Epi, bool THIN = false> ...
;     ...
;     for (int st = 0; st < ns; ++st) {
;       asm volatile("s_waitcnt vmcnt(0)" ::: "memory");
;       __builtin_amdgcn_s_barrier();
;       asm volatile("" ::: "memory");
;       if (st + 1 < ns) {
;         char* nb = smem + ((st + 1) & 1) * 65536;
;         const int ko = (st + 1) * 64;
; #pragma unroll
;         for (int i = 0; i < 4; ++i) { GLDS16(A + (size_t)(ap[i] + ko), nb + tid * 16 + i * 8192); GLDS16(Bt + (size_t)(bp[i] + ko), nb + 32768 + tid * 16 + i * 8192); }
;       }
;       const char* sa = smem + (st & 1) * 65536 + (wr * 64 + fr) * 128;
;       const char* sb = smem + (st & 1) * 65536 + 32768 + (wc * 128 + fr) * 128;
;       if constexpr (THIN) {
;         if (wc == 0) {
; #pragma unroll
;           for (int ks = 0; ks < 2; ++ks) {
;             bf16x8 af[4], bf[2];
; #pragma unroll
;             for (int m = 0; m < 4; ++m) af[m] = *(const bf16x8*)(sa + m * 2048 + (((ks * 4 + fq) ^ swz) << 4));
; #pragma unroll
;             for (int n = 0; n < 2; ++n) bf[n] = *(const bf16x8*)(sb + n * 2048 + (((ks * 4 + fq) ^ swz) << 4));
; #pragma unroll
;             for (int m = 0; m < 4; ++m)
; #pragma unroll
;               for (int n = 0; n < 2; ++n)
;                 acc[m][n] = SWAP ? __builtin_amdgcn_mfma_f32_16x16x32_bf16(bf[n], af[m], acc[m][n], 0, 0, 0)
;                                  : __builtin_amdgcn_mfma_f32_16x16x32_bf16(af[m], bf[n], acc[m][n], 0, 0, 0);
;           }
;         }
.Lthin_ns_13:
	v_readfirstlane_b32 s6, v56
	s_add_i32 m0, s6, 0x0
	v_lshl_add_u64 v[4:5], v[46:47], 0, s[64:65]
	global_load_lds_dwordx4 v[4:5], off
	v_or_b32_e32 v2, 0x3c0, v38
	s_add_i32 m0, s6, 0x8000
	v_lshl_add_u64 v[4:5], v[2:3], 1, s[18:19]
	global_load_lds_dwordx4 v[4:5], off
	s_add_i32 m0, s6, 0x2000
	v_lshl_add_u64 v[4:5], v[48:49], 0, s[64:65]
	global_load_lds_dwordx4 v[4:5], off
	s_add_i32 m0, s6, 0x4000
	v_lshl_add_u64 v[4:5], v[50:51], 0, s[64:65]
	global_load_lds_dwordx4 v[4:5], off
	s_add_i32 m0, s6, 0x6000
	v_lshl_add_u64 v[4:5], v[52:53], 0, s[64:65]
	global_load_lds_dwordx4 v[4:5], off
	s_and_saveexec_b64 s[6:7], s[4:5]
	s_cbranch_execz .LBB0_1553
	ds_read_b128 v[94:97], v87
	ds_read_b128 v[98:101], v87 offset:2048
	ds_read_b128 v[102:105], v86
	ds_read_b128 v[106:109], v86 offset:2048
	s_waitcnt lgkmcnt(0)
	v_mfma_f32_16x16x32_bf16 v[34:37], v[94:97], v[102:105], v[34:37]
	v_mfma_f32_16x16x32_bf16 v[30:33], v[98:101], v[102:105], v[30:33]
	v_mfma_f32_16x16x32_bf16 v[26:29], v[94:97], v[106:109], v[26:29]
	v_mfma_f32_16x16x32_bf16 v[22:25], v[98:101], v[106:109], v[22:25]
	ds_read_b128 v[102:105], v86 offset:4096
	ds_read_b128 v[106:109], v86 offset:6144
	s_waitcnt lgkmcnt(0)
	v_mfma_f32_16x16x32_bf16 v[18:21], v[94:97], v[102:105], v[18:21]
	v_mfma_f32_16x16x32_bf16 v[10:13], v[94:97], v[106:109], v[10:13]
	ds_read_b128 v[94:97], v89
	v_mfma_f32_16x16x32_bf16 v[14:17], v[98:101], v[102:105], v[14:17]
	v_mfma_f32_16x16x32_bf16 v[4:7], v[98:101], v[106:109], v[6:9]
	ds_read_b128 v[98:101], v89 offset:2048
	ds_read_b128 v[102:105], v88
	ds_read_b128 v[106:109], v88 offset:2048
	s_waitcnt lgkmcnt(0)
	v_mfma_f32_16x16x32_bf16 v[34:37], v[94:97], v[102:105], v[34:37]
	v_mfma_f32_16x16x32_bf16 v[30:33], v[98:101], v[102:105], v[30:33]
	v_mfma_f32_16x16x32_bf16 v[26:29], v[94:97], v[106:109], v[26:29]
	v_mfma_f32_16x16x32_bf16 v[22:25], v[98:101], v[106:109], v[22:25]
	ds_read_b128 v[102:105], v88 offset:4096
	ds_read_b128 v[106:109], v88 offset:6144
	s_waitcnt lgkmcnt(0)
	v_mfma_f32_16x16x32_bf16 v[18:21], v[94:97], v[102:105], v[18:21]
	v_mfma_f32_16x16x32_bf16 v[14:17], v[98:101], v[102:105], v[14:17]
	v_mfma_f32_16x16x32_bf16 v[10:13], v[94:97], v[106:109], v[10:13]
	v_mfma_f32_16x16x32_bf16 v[6:9], v[98:101], v[106:109], v[4:7]
